# nt cache policy on read-once f32 streams: weight loads (phases 0/1) and both x_prompt reads (phase 2 norm rows, phase 4 residual)
# speedup vs baseline: 1.0332x; 1.0158x over previous
.LBB0_28:
	v_ashrrev_i32_e32 v4, 7, v7
	v_and_b32_e32 v6, 0x3f8, v10
	v_cmp_lt_i32_e32 vcc, s13, v4
	s_and_saveexec_b64 s[10:11], vcc
	s_xor_b64 s[10:11], exec, s[10:11]
	v_mov_b64_e32 v[8:9], v[4:5]
	s_or_saveexec_b64 s[10:11], s[10:11]
	v_mov_b32_e32 v0, 0
	v_mov_b32_e32 v1, 0
	v_mov_b32_e32 v2, 0
	v_mov_b32_e32 v3, 0
	s_xor_b64 exec, exec, s[10:11]
	s_cbranch_execz .LBB0_27
	s_load_dwordx16 s[16:31], s[0:1], 0x0
	v_add_u32_e32 v0, -8, v4
	v_ashrrev_i32_e32 v9, 31, v4
	v_cmp_gt_i32_e32 vcc, 8, v4
	v_mov_b32_e32 v8, v4
	s_waitcnt lgkmcnt(0)
	v_mov_b32_e32 v2, s23
	v_mov_b32_e32 v3, s21
	v_cndmask_b32_e32 v1, 0, v9, vcc
	v_cndmask_b32_e32 v0, v0, v4, vcc
	v_cndmask_b32_e32 v3, v2, v3, vcc
	v_mov_b32_e32 v2, s22
	v_mov_b32_e32 v4, s20
	v_cndmask_b32_e32 v2, v2, v4, vcc
	v_lshlrev_b64 v[0:1], 12, v[0:1]
	v_lshl_add_u64 v[0:1], v[2:3], 0, v[0:1]
	v_lshlrev_b32_e32 v4, 2, v6
	v_lshl_add_u64 v[12:13], v[0:1], 0, v[4:5]
	global_load_dwordx4 v[0:3], v[12:13], off nt
	s_nop 0
	global_load_dwordx4 v[12:15], v[12:13], off offset:16
	s_waitcnt vmcnt(1)
	v_mul_f32_e32 v4, 0xbfb8aa3b, v0
	v_mul_f32_e32 v11, 0xbfb8aa3b, v1
	v_mul_f32_e32 v16, 0xbfb8aa3b, v2
	v_mul_f32_e32 v17, 0xbfb8aa3b, v3
	s_waitcnt vmcnt(0)
	v_mul_f32_e32 v18, 0xbfb8aa3b, v12
	v_mul_f32_e32 v19, 0xbfb8aa3b, v13
	v_mul_f32_e32 v20, 0xbfb8aa3b, v14
	v_mul_f32_e32 v21, 0xbfb8aa3b, v15
	v_exp_f32_e32 v4, v4
	v_exp_f32_e32 v11, v11
	v_exp_f32_e32 v16, v16
	v_exp_f32_e32 v17, v17
	v_exp_f32_e32 v18, v18
	v_exp_f32_e32 v19, v19
	v_exp_f32_e32 v20, v20
	v_exp_f32_e32 v21, v21
	v_add_f32_e32 v4, 1.0, v4
	v_add_f32_e32 v11, 1.0, v11
	v_add_f32_e32 v16, 1.0, v16
	v_add_f32_e32 v17, 1.0, v17
	v_add_f32_e32 v18, 1.0, v18
	v_add_f32_e32 v19, 1.0, v19
	v_add_f32_e32 v20, 1.0, v20
	v_add_f32_e32 v21, 1.0, v21
	v_rcp_f32_e32 v4, v4
	v_rcp_f32_e32 v11, v11
	v_rcp_f32_e32 v16, v16
	v_rcp_f32_e32 v17, v17
	v_rcp_f32_e32 v18, v18
	v_rcp_f32_e32 v19, v19
	v_rcp_f32_e32 v20, v20
	v_rcp_f32_e32 v21, v21
	v_mul_f32_e32 v0, v0, v4
	v_mul_f32_e32 v1, v1, v11
	v_mul_f32_e32 v2, v2, v16
	v_mul_f32_e32 v3, v3, v17
	v_mul_f32_e32 v4, v12, v18
	v_mul_f32_e32 v11, v13, v19
	v_mul_f32_e32 v12, v14, v20
	v_mul_f32_e32 v13, v15, v21
	v_cvt_pk_bf16_f32 v0, v0, v1
	v_cvt_pk_bf16_f32 v1, v2, v3
	v_cvt_pk_bf16_f32 v2, v4, v11
	v_cvt_pk_bf16_f32 v3, v12, v13
	s_branch .LBB0_27

.LBB0_250:
	v_lshrrev_b32_e32 v16, 8, v110
	v_mul_hi_i32_i24_e32 v17, 0x9000, v16
	v_mul_i32_i24_e32 v16, 0x9000, v16
	v_lshlrev_b32_e32 v86, 3, v110
	v_lshl_add_u64 v[16:17], s[96:97], 0, v[16:17]
	v_ashrrev_i32_e32 v87, 31, v86
	v_readlane_b32 s36, v254, 11
	v_lshl_add_u64 v[20:21], v[16:17], 0, s[30:31]
	v_lshlrev_b64 v[32:33], 12, v[86:87]
	v_readlane_b32 s37, v254, 12
	v_lshl_add_u64 v[18:19], v[20:21], 0, v[66:67]
	v_lshl_add_u64 v[22:23], v[20:21], 0, v[68:69]
	v_lshl_add_u64 v[32:33], s[36:37], 0, v[32:33]
	v_lshl_add_u64 v[28:29], v[16:17], 0, v[66:67]
	global_load_dwordx4 v[88:91], v[18:19], off
	s_nop 0
	global_load_dwordx4 v[16:19], v[28:29], off
	global_load_dwordx4 v[92:95], v[22:23], off
	v_lshl_add_u64 v[22:23], v[20:21], 0, v[70:71]
	v_lshl_add_u64 v[20:21], v[20:21], 0, v[72:73]
	v_lshl_add_u64 v[32:33], v[32:33], 0, v[82:83]
	global_load_dwordx4 v[96:99], v[22:23], off
	global_load_dwordx4 v[100:103], v[20:21], off
	s_nop 0
	global_load_dwordx4 v[20:23], v[28:29], off offset:1024
	global_load_dwordx4 v[24:27], v[28:29], off offset:2048
	s_nop 0
	global_load_dwordx4 v[28:31], v[28:29], off offset:3072
	s_nop 0
	global_load_dwordx4 v[60:63], v[32:33], off nt
	global_load_dwordx4 v[56:59], v[32:33], off offset:1024 nt
	global_load_dwordx4 v[44:47], v[32:33], off offset:2048 nt
	global_load_dwordx4 v[36:39], v[32:33], off offset:3072 nt
	v_ashrrev_i32_e32 v81, 31, v80
	v_readlane_b32 s48, v254, 23
	v_readlane_b32 s49, v254, 24
	v_readlane_b32 s50, v254, 25
	v_readlane_b32 s51, v254, 26
	v_mov_b32_e32 v32, 0
	v_lshlrev_b64 v[84:85], 12, v[80:81]
	v_lshlrev_b64 v[86:87], 11, v[86:87]
	s_mov_b64 s[48:49], 0
	s_mov_b64 s[50:51], 0
	v_mov_b32_e32 v33, v32
	v_mov_b32_e32 v34, v32
	v_mov_b32_e32 v35, v32
	v_mov_b32_e32 v40, v32
	v_mov_b32_e32 v41, v32
	v_mov_b32_e32 v42, v32
	v_mov_b32_e32 v43, v32
	v_mov_b32_e32 v48, v32
	v_mov_b32_e32 v49, v32
	v_mov_b32_e32 v50, v32
	v_mov_b32_e32 v51, v32
	v_mov_b32_e32 v52, v32
	v_mov_b32_e32 v53, v32
	v_mov_b32_e32 v54, v32
	v_lshl_add_u64 v[84:85], v[78:79], 0, v[84:85]
	v_lshl_add_u64 v[86:87], v[76:77], 0, v[86:87]
	v_mov_b32_e32 v55, v32
	v_readlane_b32 s38, v254, 13
	v_readlane_b32 s39, v254, 14
	v_readlane_b32 s40, v254, 15
	v_readlane_b32 s41, v254, 16
	v_readlane_b32 s42, v254, 17
	v_readlane_b32 s43, v254, 18
	v_readlane_b32 s44, v254, 19
	v_readlane_b32 s45, v254, 20
	v_readlane_b32 s46, v254, 21
	v_readlane_b32 s47, v254, 22
	s_waitcnt vmcnt(11)
	v_pk_add_f32 v[90:91], v[90:91], 1.0 op_sel_hi:[1,0]
	v_pk_add_f32 v[112:113], v[88:89], 1.0 op_sel_hi:[1,0]
	s_waitcnt vmcnt(9)
	v_pk_add_f32 v[94:95], v[94:95], 1.0 op_sel_hi:[1,0]
	v_pk_add_f32 v[114:115], v[92:93], 1.0 op_sel_hi:[1,0]
	s_waitcnt vmcnt(8)
	v_pk_add_f32 v[98:99], v[98:99], 1.0 op_sel_hi:[1,0]
	v_pk_add_f32 v[116:117], v[96:97], 1.0 op_sel_hi:[1,0]
	s_waitcnt vmcnt(7)
	v_pk_add_f32 v[102:103], v[102:103], 1.0 op_sel_hi:[1,0]
	v_pk_add_f32 v[118:119], v[100:101], 1.0 op_sel_hi:[1,0]
	v_pk_mul_f32 v[88:89], v[2:3], v[90:91]
	v_pk_mul_f32 v[90:91], v[0:1], v[112:113]
	v_pk_mul_f32 v[92:93], v[6:7], v[94:95]
	v_pk_mul_f32 v[94:95], v[4:5], v[114:115]
	v_pk_mul_f32 v[96:97], v[10:11], v[98:99]
	v_pk_mul_f32 v[98:99], v[8:9], v[116:117]
	v_pk_mul_f32 v[100:101], v[14:15], v[102:103]
	v_pk_mul_f32 v[102:103], v[12:13], v[118:119]
	s_branch .LBB0_252

.LBB0_252:
	s_cmpk_eq_i32 s50, 0x7000
	s_mov_b64 s[6:7], 0x1c00
	s_cbranch_scc1 .LBB0_251
	v_lshl_add_u64 v[32:33], v[84:85], 0, s[50:51]
	v_add_co_u32_e32 v52, vcc, 0x1000, v32
	s_mov_b64 s[6:7], s[48:49]
	s_nop 0
	v_addc_co_u32_e32 v53, vcc, 0, v33, vcc
	global_load_dwordx4 v[32:35], v[52:53], off nt
	global_load_dwordx4 v[40:43], v[52:53], off offset:1024 nt
	global_load_dwordx4 v[48:51], v[52:53], off offset:2048 nt
	s_nop 0
	global_load_dwordx4 v[52:55], v[52:53], off offset:3072 nt
	s_branch .LBB0_251

.LBB0_435:
	s_ashr_i32 s6, s47, 3
	s_mul_hi_i32 s7, s6, 0x9000
	s_mul_i32 s6, s6, 0x9000
	s_add_u32 s6, s50, s6
	s_addc_u32 s7, s51, s7
	v_lshl_add_u64 v[164:165], v[146:147], 2, s[6:7]
	global_load_dwordx4 v[148:151], v[164:165], off offset:16
	global_load_dwordx4 v[152:155], v[164:165], off
	s_lshl_b32 s6, s47, 8
	v_readlane_b32 s72, v254, 11
	v_readlane_b32 s73, v254, 12
	v_readlane_b32 s74, v254, 13
	v_readlane_b32 s75, v254, 14
	v_readlane_b32 s76, v254, 15
	v_readlane_b32 s77, v254, 16
	v_readlane_b32 s78, v254, 17
	v_readlane_b32 s79, v254, 18
	v_readlane_b32 s80, v254, 19
	v_readlane_b32 s81, v254, 20
	v_readlane_b32 s82, v254, 21
	v_readlane_b32 s83, v254, 22
	v_readlane_b32 s84, v254, 23
	v_readlane_b32 s85, v254, 24
	v_readlane_b32 s86, v254, 25
	v_readlane_b32 s87, v254, 26
	s_waitcnt vmcnt(0)
	v_pk_mul_f32 v[160:161], v[150:151], 0.5 op_sel_hi:[1,0]
	v_pk_mul_f32 v[162:163], v[148:149], 0.5 op_sel_hi:[1,0]
	global_load_dwordx4 v[176:179], v[164:165], off offset:528
	global_load_dwordx4 v[148:151], v[164:165], off offset:512
	v_add_u32_e32 v164, s6, v167
	v_ashrrev_i32_e32 v165, 31, v164
	v_pk_mul_f32 v[158:159], v[152:153], 0.5 op_sel_hi:[1,0]
	v_pk_mul_f32 v[156:157], v[154:155], 0.5 op_sel_hi:[1,0]
	s_waitcnt vmcnt(0)
	v_pk_mul_f32 v[152:153], v[150:151], 0.5 op_sel_hi:[1,0]
	v_pk_mul_f32 v[150:151], v[176:177], 0.5 op_sel_hi:[1,0]
	v_lshlrev_b64 v[176:177], 10, v[164:165]
	v_lshl_add_u64 v[208:209], v[176:177], 0, v[146:147]
	v_lshl_add_u64 v[200:201], v[208:209], 2, s[72:73]
	v_pk_mul_f32 v[154:155], v[148:149], 0.5 op_sel_hi:[1,0]
	v_pk_mul_f32 v[148:149], v[178:179], 0.5 op_sel_hi:[1,0]
	global_load_dwordx4 v[176:179], v[200:201], off offset:16 nt
	global_load_dwordx4 v[180:183], v[200:201], off nt
	global_load_dwordx4 v[184:187], v[200:201], off offset:528 nt
	global_load_dwordx4 v[188:191], v[200:201], off offset:512 nt
	v_add_co_u32_e32 v202, vcc, s14, v200
	v_lshl_add_u64 v[196:197], v[200:201], 0, s[58:59]
	s_nop 0
	v_addc_co_u32_e32 v203, vcc, 0, v201, vcc
	global_load_dwordx4 v[192:195], v[202:203], off nt
	s_nop 0
	global_load_dwordx4 v[196:199], v[196:197], off offset:16 nt
	v_lshl_add_u64 v[204:205], v[200:201], 0, s[94:95]
	global_load_dwordx4 v[200:203], v[202:203], off offset:512 nt
	s_nop 0
	global_load_dwordx4 v[204:207], v[204:205], off offset:16 nt
	s_waitcnt vmcnt(7)
	v_pk_fma_f32 v[178:179], v[122:123], v[160:161], v[178:179]
	s_waitcnt vmcnt(6)
	v_pk_fma_f32 v[124:125], v[124:125], v[158:159], v[180:181]
	v_pk_fma_f32 v[126:127], v[126:127], v[156:157], v[182:183]
	v_pk_fma_f32 v[122:123], v[120:121], v[162:163], v[176:177]
	v_cvt_pk_bf16_f32 v120, v124, v125
	v_cvt_pk_bf16_f32 v121, v126, v127
	v_lshl_add_u64 v[124:125], v[208:209], 1, s[22:23]
	v_cvt_pk_bf16_f32 v122, v122, v123
	v_cvt_pk_bf16_f32 v123, v178, v179
	global_store_dwordx4 v[124:125], v[120:123], off
	s_waitcnt vmcnt(5)
	v_pk_fma_f32 v[110:111], v[110:111], v[152:153], v[190:191]
	v_pk_fma_f32 v[108:109], v[108:109], v[154:155], v[188:189]
	v_pk_fma_f32 v[120:121], v[106:107], v[148:149], v[186:187]
	v_pk_fma_f32 v[106:107], v[104:105], v[150:151], v[184:185]
	v_cvt_pk_bf16_f32 v104, v108, v109
	v_cvt_pk_bf16_f32 v105, v110, v111
	s_waitcnt vmcnt(3)
	v_pk_fma_f32 v[108:109], v[114:115], v[160:161], v[198:199]
	v_cvt_pk_bf16_f32 v106, v106, v107
	v_cvt_pk_bf16_f32 v107, v120, v121
	global_store_dwordx4 v[124:125], v[104:107], off offset:256
	v_pk_fma_f32 v[110:111], v[112:113], v[162:163], v[196:197]
	s_waitcnt vmcnt(3)
	v_pk_fma_f32 v[100:101], v[100:101], v[154:155], v[200:201]
	v_pk_fma_f32 v[106:107], v[118:119], v[156:157], v[194:195]
	v_pk_fma_f32 v[104:105], v[116:117], v[158:159], v[192:193]
	v_pk_fma_f32 v[102:103], v[102:103], v[152:153], v[202:203]
	v_cvt_pk_bf16_f32 v104, v104, v105
	v_cvt_pk_bf16_f32 v105, v106, v107
	v_cvt_pk_bf16_f32 v106, v110, v111
	v_cvt_pk_bf16_f32 v107, v108, v109
	v_add_co_u32_e32 v108, vcc, s17, v124
	s_nop 1
	v_addc_co_u32_e32 v109, vcc, 0, v125, vcc
	global_store_dwordx4 v[108:109], v[104:107], off
	s_waitcnt vmcnt(3)
	s_nop 0
	v_pk_fma_f32 v[104:105], v[98:99], v[148:149], v[206:207]
	v_pk_fma_f32 v[98:99], v[96:97], v[150:151], v[204:205]
	v_cvt_pk_bf16_f32 v96, v100, v101
	v_cvt_pk_bf16_f32 v97, v102, v103
	s_nop 0
	v_cvt_pk_bf16_f32 v98, v98, v99
	v_cvt_pk_bf16_f32 v99, v104, v105
	global_store_dwordx4 v[108:109], v[96:99], off offset:256
	s_nop 1
	v_add_u32_e32 v96, s6, v169
	v_ashrrev_i32_e32 v97, 31, v96
	v_lshlrev_b64 v[96:97], 10, v[96:97]
	v_lshl_add_u64 v[176:177], v[96:97], 0, v[146:147]
	v_lshl_add_u64 v[120:121], v[176:177], 2, s[72:73]
	global_load_dwordx4 v[96:99], v[120:121], off offset:16 nt
	global_load_dwordx4 v[100:103], v[120:121], off nt
	global_load_dwordx4 v[104:107], v[120:121], off offset:528 nt
	global_load_dwordx4 v[108:111], v[120:121], off offset:512 nt
	v_add_co_u32_e32 v122, vcc, s14, v120
	v_lshl_add_u64 v[116:117], v[120:121], 0, s[58:59]
	s_nop 0
	v_addc_co_u32_e32 v123, vcc, 0, v121, vcc
	global_load_dwordx4 v[112:115], v[122:123], off nt
	s_nop 0
	global_load_dwordx4 v[116:119], v[116:117], off offset:16 nt
	v_lshl_add_u64 v[124:125], v[120:121], 0, s[94:95]
	global_load_dwordx4 v[120:123], v[122:123], off offset:512 nt
	s_nop 0
	global_load_dwordx4 v[124:127], v[124:125], off offset:16 nt
	s_waitcnt vmcnt(7)
	v_pk_fma_f32 v[98:99], v[90:91], v[160:161], v[98:99]
	s_waitcnt vmcnt(6)
	v_pk_fma_f32 v[92:93], v[92:93], v[158:159], v[100:101]
	v_pk_fma_f32 v[94:95], v[94:95], v[156:157], v[102:103]
	v_pk_fma_f32 v[90:91], v[88:89], v[162:163], v[96:97]
	v_cvt_pk_bf16_f32 v88, v92, v93
	v_cvt_pk_bf16_f32 v89, v94, v95
	v_lshl_add_u64 v[92:93], v[176:177], 1, s[22:23]
	v_cvt_pk_bf16_f32 v90, v90, v91
	v_cvt_pk_bf16_f32 v91, v98, v99
	global_store_dwordx4 v[92:93], v[88:91], off
	s_waitcnt vmcnt(5)
	v_pk_fma_f32 v[78:79], v[78:79], v[152:153], v[110:111]
	v_pk_fma_f32 v[76:77], v[76:77], v[154:155], v[108:109]
	v_pk_fma_f32 v[88:89], v[74:75], v[148:149], v[106:107]
	v_pk_fma_f32 v[74:75], v[72:73], v[150:151], v[104:105]
	v_cvt_pk_bf16_f32 v72, v76, v77
	v_cvt_pk_bf16_f32 v73, v78, v79
	s_waitcnt vmcnt(3)
	v_pk_fma_f32 v[76:77], v[82:83], v[160:161], v[118:119]
	v_cvt_pk_bf16_f32 v74, v74, v75
	v_cvt_pk_bf16_f32 v75, v88, v89
	global_store_dwordx4 v[92:93], v[72:75], off offset:256
	v_pk_fma_f32 v[78:79], v[80:81], v[162:163], v[116:117]
	s_waitcnt vmcnt(3)
	v_pk_fma_f32 v[68:69], v[68:69], v[154:155], v[120:121]
	v_pk_fma_f32 v[74:75], v[86:87], v[156:157], v[114:115]
	v_pk_fma_f32 v[72:73], v[84:85], v[158:159], v[112:113]
	v_pk_fma_f32 v[70:71], v[70:71], v[152:153], v[122:123]
	v_cvt_pk_bf16_f32 v72, v72, v73
	v_cvt_pk_bf16_f32 v73, v74, v75
	v_cvt_pk_bf16_f32 v74, v78, v79
	v_cvt_pk_bf16_f32 v75, v76, v77
	v_add_co_u32_e32 v76, vcc, s17, v92
	s_nop 1
	v_addc_co_u32_e32 v77, vcc, 0, v93, vcc
	global_store_dwordx4 v[76:77], v[72:75], off
	s_waitcnt vmcnt(3)
	s_nop 0
	v_pk_fma_f32 v[72:73], v[66:67], v[148:149], v[126:127]
	v_pk_fma_f32 v[66:67], v[64:65], v[150:151], v[124:125]
	v_cvt_pk_bf16_f32 v64, v68, v69
	v_cvt_pk_bf16_f32 v65, v70, v71
	s_nop 0
	v_cvt_pk_bf16_f32 v66, v66, v67
	v_cvt_pk_bf16_f32 v67, v72, v73
	global_store_dwordx4 v[76:77], v[64:67], off offset:256
	s_nop 1
	v_add_u32_e32 v64, 0x80, v164
	v_ashrrev_i32_e32 v65, 31, v64
	v_lshlrev_b64 v[64:65], 10, v[64:65]
	v_lshl_add_u64 v[96:97], v[64:65], 0, v[146:147]
	v_lshl_add_u64 v[88:89], v[96:97], 2, s[72:73]
	global_load_dwordx4 v[64:67], v[88:89], off offset:16 nt
	global_load_dwordx4 v[68:71], v[88:89], off nt
	global_load_dwordx4 v[72:75], v[88:89], off offset:528 nt
	global_load_dwordx4 v[76:79], v[88:89], off offset:512 nt
	v_add_co_u32_e32 v90, vcc, s14, v88
	v_lshl_add_u64 v[84:85], v[88:89], 0, s[58:59]
	s_nop 0
	v_addc_co_u32_e32 v91, vcc, 0, v89, vcc
	global_load_dwordx4 v[80:83], v[90:91], off nt
	s_nop 0
	global_load_dwordx4 v[84:87], v[84:85], off offset:16 nt
	v_lshl_add_u64 v[92:93], v[88:89], 0, s[94:95]
	global_load_dwordx4 v[88:91], v[90:91], off offset:512 nt
	s_nop 0
	global_load_dwordx4 v[92:95], v[92:93], off offset:16 nt
	s_waitcnt vmcnt(7)
	v_pk_fma_f32 v[66:67], v[58:59], v[160:161], v[66:67]
	s_waitcnt vmcnt(6)
	v_pk_fma_f32 v[60:61], v[60:61], v[158:159], v[68:69]
	v_pk_fma_f32 v[62:63], v[62:63], v[156:157], v[70:71]
	v_pk_fma_f32 v[58:59], v[56:57], v[162:163], v[64:65]
	v_cvt_pk_bf16_f32 v56, v60, v61
	v_cvt_pk_bf16_f32 v57, v62, v63
	v_lshl_add_u64 v[60:61], v[96:97], 1, s[22:23]
	v_cvt_pk_bf16_f32 v58, v58, v59
	v_cvt_pk_bf16_f32 v59, v66, v67
	global_store_dwordx4 v[60:61], v[56:59], off
	s_waitcnt vmcnt(5)
	v_pk_fma_f32 v[46:47], v[46:47], v[152:153], v[78:79]
	v_pk_fma_f32 v[44:45], v[44:45], v[154:155], v[76:77]
	v_pk_fma_f32 v[56:57], v[42:43], v[148:149], v[74:75]
	v_pk_fma_f32 v[42:43], v[40:41], v[150:151], v[72:73]
	v_cvt_pk_bf16_f32 v40, v44, v45
	v_cvt_pk_bf16_f32 v41, v46, v47
	s_waitcnt vmcnt(3)
	v_pk_fma_f32 v[44:45], v[50:51], v[160:161], v[86:87]
	v_cvt_pk_bf16_f32 v42, v42, v43
	v_cvt_pk_bf16_f32 v43, v56, v57
	global_store_dwordx4 v[60:61], v[40:43], off offset:256
	v_pk_fma_f32 v[46:47], v[48:49], v[162:163], v[84:85]
	s_waitcnt vmcnt(3)
	v_pk_fma_f32 v[36:37], v[36:37], v[154:155], v[88:89]
	v_pk_fma_f32 v[42:43], v[54:55], v[156:157], v[82:83]
	v_pk_fma_f32 v[40:41], v[52:53], v[158:159], v[80:81]
	v_pk_fma_f32 v[38:39], v[38:39], v[152:153], v[90:91]
	v_cvt_pk_bf16_f32 v40, v40, v41
	v_cvt_pk_bf16_f32 v41, v42, v43
	v_cvt_pk_bf16_f32 v42, v46, v47
	v_cvt_pk_bf16_f32 v43, v44, v45
	v_add_co_u32_e32 v44, vcc, s17, v60
	s_nop 1
	v_addc_co_u32_e32 v45, vcc, 0, v61, vcc
	global_store_dwordx4 v[44:45], v[40:43], off
	s_waitcnt vmcnt(3)
	s_nop 0
	v_pk_fma_f32 v[40:41], v[34:35], v[148:149], v[94:95]
	v_pk_fma_f32 v[34:35], v[32:33], v[150:151], v[92:93]
	v_cvt_pk_bf16_f32 v32, v36, v37
	v_cvt_pk_bf16_f32 v33, v38, v39
	s_nop 0
	v_cvt_pk_bf16_f32 v34, v34, v35
	v_cvt_pk_bf16_f32 v35, v40, v41
	global_store_dwordx4 v[44:45], v[32:35], off offset:256
	s_nop 1
	v_add_u32_e32 v32, 0xa0, v164
	v_ashrrev_i32_e32 v33, 31, v32
	v_lshlrev_b64 v[32:33], 10, v[32:33]
	v_lshl_add_u64 v[64:65], v[32:33], 0, v[146:147]
	v_lshl_add_u64 v[56:57], v[64:65], 2, s[72:73]
	global_load_dwordx4 v[32:35], v[56:57], off offset:16 nt
	global_load_dwordx4 v[36:39], v[56:57], off nt
	global_load_dwordx4 v[40:43], v[56:57], off offset:528 nt
	global_load_dwordx4 v[44:47], v[56:57], off offset:512 nt
	v_add_co_u32_e32 v58, vcc, s14, v56
	v_lshl_add_u64 v[52:53], v[56:57], 0, s[58:59]
	s_nop 0
	v_addc_co_u32_e32 v59, vcc, 0, v57, vcc
	global_load_dwordx4 v[48:51], v[58:59], off nt
	s_nop 0
	global_load_dwordx4 v[52:55], v[52:53], off offset:16 nt
	v_lshl_add_u64 v[60:61], v[56:57], 0, s[94:95]
	global_load_dwordx4 v[56:59], v[58:59], off offset:512 nt
	s_nop 0
	global_load_dwordx4 v[60:63], v[60:61], off offset:16 nt
	s_waitcnt vmcnt(7)
	v_pk_fma_f32 v[34:35], v[26:27], v[160:161], v[34:35]
	s_waitcnt vmcnt(6)
	v_pk_fma_f32 v[28:29], v[28:29], v[158:159], v[36:37]
	v_pk_fma_f32 v[30:31], v[30:31], v[156:157], v[38:39]
	v_pk_fma_f32 v[26:27], v[24:25], v[162:163], v[32:33]
	v_cvt_pk_bf16_f32 v24, v28, v29
	v_cvt_pk_bf16_f32 v25, v30, v31
	v_lshl_add_u64 v[28:29], v[64:65], 1, s[22:23]
	v_cvt_pk_bf16_f32 v26, v26, v27
	v_cvt_pk_bf16_f32 v27, v34, v35
	global_store_dwordx4 v[28:29], v[24:27], off
	s_waitcnt vmcnt(5)
	v_pk_fma_f32 v[14:15], v[14:15], v[152:153], v[46:47]
	v_pk_fma_f32 v[12:13], v[12:13], v[154:155], v[44:45]
	v_pk_fma_f32 v[24:25], v[10:11], v[148:149], v[42:43]
	v_pk_fma_f32 v[10:11], v[8:9], v[150:151], v[40:41]
	v_cvt_pk_bf16_f32 v8, v12, v13
	v_cvt_pk_bf16_f32 v9, v14, v15
	s_waitcnt vmcnt(3)
	v_pk_fma_f32 v[12:13], v[18:19], v[160:161], v[54:55]
	v_cvt_pk_bf16_f32 v10, v10, v11
	v_cvt_pk_bf16_f32 v11, v24, v25
	global_store_dwordx4 v[28:29], v[8:11], off offset:256
	v_pk_fma_f32 v[14:15], v[16:17], v[162:163], v[52:53]
	s_waitcnt vmcnt(3)
	v_pk_fma_f32 v[6:7], v[6:7], v[152:153], v[58:59]
	v_pk_fma_f32 v[10:11], v[22:23], v[156:157], v[50:51]
	v_pk_fma_f32 v[8:9], v[20:21], v[158:159], v[48:49]
	v_pk_fma_f32 v[4:5], v[4:5], v[154:155], v[56:57]
	v_cvt_pk_bf16_f32 v8, v8, v9
	v_cvt_pk_bf16_f32 v9, v10, v11
	v_cvt_pk_bf16_f32 v10, v14, v15
	v_cvt_pk_bf16_f32 v11, v12, v13
	v_add_co_u32_e32 v12, vcc, s17, v28
	s_nop 1
	v_addc_co_u32_e32 v13, vcc, 0, v29, vcc
	global_store_dwordx4 v[12:13], v[8:11], off
	s_waitcnt vmcnt(3)
	s_nop 0
	v_pk_fma_f32 v[8:9], v[2:3], v[148:149], v[62:63]
	v_pk_fma_f32 v[2:3], v[0:1], v[150:151], v[60:61]
	v_cvt_pk_bf16_f32 v0, v4, v5
	v_cvt_pk_bf16_f32 v1, v6, v7
	s_nop 0
	v_cvt_pk_bf16_f32 v2, v2, v3
	v_cvt_pk_bf16_f32 v3, v8, v9
	global_store_dwordx4 v[12:13], v[0:3], off offset:256
	s_and_b64 vcc, exec, s[4:5]
	s_mov_b64 s[4:5], -1
	s_cbranch_vccnz .LBB0_407
